# layer-0 PEER apply: the 512 context rows dealt two per workgroup (waves 0,1) instead of to the first 64 workgroups
# speedup vs baseline: 1.0048x; 1.0041x over previous
; __device__ __forceinline__ void ph_peer_apply(const Params& P, int layer, float* xlat, float* xctx_in, float* xctx_out, int nrows, bool write_next, char* smem, float* xlat_out = nullptr) {
;     ...
;   for (int row = blockIdx.x * (NTHR / 64) + wave; row < nrows; row += gridDim.x * (NTHR / 64)) {
;     float xv[32];
; #pragma unroll
;     for (int j8 = 0; j8 < 4; ++j8) {
;       const h16x8 t = *(const h16x8*)(xq + (size_t)row * D + lb * 32 + j8 * 8);
; #pragma unroll
;       for (int j = 0; j < 8; ++j) xv[j8 * 8 + j] = lact ? (float)t[j] : 0.f;
;     }
;     const int id0 = seli[(size_t)row * NSEL + lane], id1 = seli[(size_t)row * NSEL + 64 + lane];
;     const float g0 = selg[(size_t)row * NSEL + lane], g1 = selg[(size_t)row * NSEL + 64 + lane];
;     float a0 = 0.f, a1 = 0.f;
;     P6Blk bufA[PB_G], bufB[PB_G];
.Lau0_ntl:
	s_add_u32 s50, s50, 1
	s_add_u32 s1, s1, s44
	s_cmp_lt_u32 s1, 0x8200
	s_cbranch_scc1 .Lau0_ntl
	s_lshl_b32 s14, s44, 4
	s_add_u32 s14, s14, s13
	s_cmp_lg_u32 s84, 0x100
	s_cbranch_scc1 .Lax0_u
	s_lshr_b32 s14, s60, 2
	s_add_u32 s14, s14, s12
	s_add_u32 s14, s14, 0x8000
	s_cmp_lt_u32 s12, 2
	s_cselect_b32 s50, 17, 16
	.Lax0_u:
	s_mov_b32 s58, 0
	s_mov_b32 s59, 0
	s_mov_b32 s62, 0
	s_mov_b32 s48, 0
	s_mov_b32 s49, 0
	s_mov_b32 s45, s13
	s_lshl_b32 s15, s45, 12
	s_lshr_b32 s31, s45, 20
	s_add_u32 s20, s4, 0xbe4c000
	s_addc_u32 s21, s5, 0
	s_add_u32 s20, s20, s15
	s_addc_u32 s21, s21, s31
	s_lshl_b32 s15, s45, 9
	s_add_u32 s22, s4, 0x1404c000
	s_addc_u32 s23, s5, 0
	s_add_u32 s22, s22, s15
	s_addc_u32 s23, s23, 0
	global_load_dwordx4 v[230:233], v224, s[20:21]
	global_load_dwordx4 v[234:237], v224, s[20:21] offset:16
	global_load_dwordx4 v[238:241], v224, s[20:21] offset:32
	global_load_dwordx4 v[242:245], v224, s[20:21] offset:48
	global_load_dword v36, v226, s[22:23]
	global_load_dword v37, v226, s[22:23] offset:256
	s_waitcnt vmcnt(0)
	v_cvt_f32_f16_e32 v4, v230
	v_cvt_f32_f16_sdwa v5, v230 dst_sel:DWORD dst_unused:UNUSED_PAD src0_sel:WORD_1
	v_cvt_f32_f16_e32 v6, v231
	v_cvt_f32_f16_sdwa v7, v231 dst_sel:DWORD dst_unused:UNUSED_PAD src0_sel:WORD_1
	v_cvt_f32_f16_e32 v8, v232
	v_cvt_f32_f16_sdwa v9, v232 dst_sel:DWORD dst_unused:UNUSED_PAD src0_sel:WORD_1
	v_cvt_f32_f16_e32 v10, v233
	v_cvt_f32_f16_sdwa v11, v233 dst_sel:DWORD dst_unused:UNUSED_PAD src0_sel:WORD_1
	v_cvt_f32_f16_e32 v12, v234
	v_cvt_f32_f16_sdwa v13, v234 dst_sel:DWORD dst_unused:UNUSED_PAD src0_sel:WORD_1
	v_cvt_f32_f16_e32 v14, v235
	v_cvt_f32_f16_sdwa v15, v235 dst_sel:DWORD dst_unused:UNUSED_PAD src0_sel:WORD_1
	v_cvt_f32_f16_e32 v16, v236
	v_cvt_f32_f16_sdwa v17, v236 dst_sel:DWORD dst_unused:UNUSED_PAD src0_sel:WORD_1
	v_cvt_f32_f16_e32 v18, v237
	v_cvt_f32_f16_sdwa v19, v237 dst_sel:DWORD dst_unused:UNUSED_PAD src0_sel:WORD_1
	v_cvt_f32_f16_e32 v20, v238
	v_cvt_f32_f16_sdwa v21, v238 dst_sel:DWORD dst_unused:UNUSED_PAD src0_sel:WORD_1
	v_cvt_f32_f16_e32 v22, v239
	v_cvt_f32_f16_sdwa v23, v239 dst_sel:DWORD dst_unused:UNUSED_PAD src0_sel:WORD_1
	v_cvt_f32_f16_e32 v24, v240
	v_cvt_f32_f16_sdwa v25, v240 dst_sel:DWORD dst_unused:UNUSED_PAD src0_sel:WORD_1
	v_cvt_f32_f16_e32 v26, v241
	v_cvt_f32_f16_sdwa v27, v241 dst_sel:DWORD dst_unused:UNUSED_PAD src0_sel:WORD_1
	v_cvt_f32_f16_e32 v28, v242
	v_cvt_f32_f16_sdwa v29, v242 dst_sel:DWORD dst_unused:UNUSED_PAD src0_sel:WORD_1
	v_cvt_f32_f16_e32 v30, v243
	v_cvt_f32_f16_sdwa v31, v243 dst_sel:DWORD dst_unused:UNUSED_PAD src0_sel:WORD_1
	v_cvt_f32_f16_e32 v32, v244
	v_cvt_f32_f16_sdwa v33, v244 dst_sel:DWORD dst_unused:UNUSED_PAD src0_sel:WORD_1
	v_cvt_f32_f16_e32 v34, v245
	v_cvt_f32_f16_sdwa v35, v245 dst_sel:DWORD dst_unused:UNUSED_PAD src0_sel:WORD_1
	v_lshrrev_b32_e32 v249, 11, v36
	v_lshrrev_b32_e32 v250, 11, v37
	v_cmp_eq_u32_e64 s[52:53], s58, v249
	v_cmp_eq_u32_e64 s[54:55], s58, v250
	v_mul_u32_u24_e32 v44, 0x640, v36
	s_mov_b32 s61, 0
	s_lshl_b32 s63, s59, 9
	s_mul_i32 s1, s12, 0x2800
	s_add_u32 s63, s63, s1
	v_add_u32_e32 v46, s63, v226
	s_bcnt1_i32_b64 s1, s[52:53]
	s_bcnt1_i32_b64 s15, s[54:55]
	s_add_u32 s1, s1, s15
	s_sub_u32 s57, 8, s1
	s_cselect_b32 s57, 0, s57
	s_add_u32 s1, s59, 1
	s_cmp_lt_u32 s1, s50
	s_cbranch_scc1 .Lau0_pfki
	s_mov_b32 s1, 0
	s_cmp_lt_u32 s58, 7
	s_cbranch_scc0 .Lau0_pfdi
.Lau0_pfki:
	s_mul_i32 s15, s1, s44
	s_add_u32 s15, s15, s13
	s_cmp_eq_u32 s1, 16
	s_cselect_b32 s1, s14, s15
	s_lshl_b32 s15, s1, 12
	s_lshr_b32 s31, s1, 20
	s_add_u32 s20, s4, 0xbe4c000
	s_addc_u32 s21, s5, 0
	s_add_u32 s20, s20, s15
	s_addc_u32 s21, s21, s31
	s_lshl_b32 s15, s1, 9
	s_add_u32 s22, s4, 0x1404c000
	s_addc_u32 s23, s5, 0
	s_add_u32 s22, s22, s15
	s_addc_u32 s23, s23, 0
	global_load_dword v38, v226, s[22:23]
	global_load_dword v39, v226, s[22:23] offset:256
	global_load_dwordx4 v[230:233], v224, s[20:21]
	global_load_dwordx4 v[234:237], v224, s[20:21] offset:16
	global_load_dwordx4 v[238:241], v224, s[20:21] offset:32
	global_load_dwordx4 v[242:245], v224, s[20:21] offset:48

; #define PB_FENCE asm volatile("" ::: "memory")
; __device__ __forceinline__ void ph_peer_apply(const Params& P, int layer, float* xlat, float* xctx_in, float* xctx_out, int nrows, bool write_next, char* smem, float* xlat_out = nullptr) {
;     ...
;     const int id0 = seli[(size_t)row * NSEL + lane], id1 = seli[(size_t)row * NSEL + 64 + lane];
;     const float g0 = selg[(size_t)row * NSEL + lane], g1 = selg[(size_t)row * NSEL + 64 + lane];
;     ...
;     PB_LOAD(bufA, tv, 0);
;     for (int gq = 0; gq < NG; gq += 2) {
;       PB_LOAD(bufB, tv, gq + 1); PB_FENCE;
;       PB_ACC(bufA, gq);
;       if (gq + 2 < NG) PB_LOAD(bufA, tv, gq + 2);
;       PB_FENCE;
;       PB_ACC(bufB, gq + 1);
;     }
.Lav0_ntl:
	s_add_u32 s62, s62, 1
	s_add_u32 s1, s1, s44
	s_cmp_lt_u32 s1, 0x8200
	s_cbranch_scc1 .Lav0_ntl
	s_lshl_b32 s14, s44, 4
	s_add_u32 s14, s14, s13
	s_cmp_lg_u32 s84, 0x100
	s_cbranch_scc1 .Lax0_v
	s_lshr_b32 s14, s60, 2
	s_add_u32 s14, s14, s12
	s_add_u32 s14, s14, 0x8000
	s_cmp_lt_u32 s12, 2
	s_cselect_b32 s62, 17, 16
	.Lax0_v:
	s_mov_b32 s51, 0
.Lav0_group:
	s_sub_u32 s57, s62, s51
	s_min_u32 s57, s57, 4
	s_add_u32 s1, s51, 0
	s_lshl_b32 s31, s1, 9
	s_mul_i32 s15, s1, s44
	s_add_u32 s15, s15, s13
	s_cmp_eq_u32 s1, 16
	s_cselect_b32 s1, s14, s15
	s_lshl_b32 s15, s1, 9
	s_add_u32 s22, s4, 0x1404c000
	s_addc_u32 s23, s5, 0
	s_add_u32 s22, s22, s15
	s_addc_u32 s23, s23, 0
	global_load_dword v36, v226, s[22:23]
	global_load_dword v37, v226, s[22:23] offset:256
	s_add_u32 s24, s4, 0x1508c000
	s_addc_u32 s25, s5, 0
	s_add_u32 s24, s24, s15
	s_addc_u32 s25, s25, 0
	global_load_dword v114, v226, s[24:25]
	global_load_dword v115, v226, s[24:25] offset:256
	v_add_u32_e32 v229, s31, v228
	ds_read_b32 v112, v229
	ds_read_b32 v113, v229 offset:256
	s_cmp_le_u32 s57, 1
	s_cbranch_scc1 .Lav0_ldd
	s_add_u32 s1, s51, 1
	s_lshl_b32 s31, s1, 9
	s_mul_i32 s15, s1, s44
	s_add_u32 s15, s15, s13
	s_cmp_eq_u32 s1, 16
	s_cselect_b32 s1, s14, s15
	s_lshl_b32 s15, s1, 9
	s_add_u32 s22, s4, 0x1404c000
	s_addc_u32 s23, s5, 0
	s_add_u32 s22, s22, s15
	s_addc_u32 s23, s23, 0
	global_load_dword v38, v226, s[22:23]
	global_load_dword v39, v226, s[22:23] offset:256
	s_add_u32 s24, s4, 0x1508c000
	s_addc_u32 s25, s5, 0
	s_add_u32 s24, s24, s15
	s_addc_u32 s25, s25, 0
	global_load_dword v116, v226, s[24:25]
	global_load_dword v117, v226, s[24:25] offset:256
	v_add_u32_e32 v229, s31, v228
	ds_read_b32 v146, v229
	ds_read_b32 v147, v229 offset:256
	s_cmp_le_u32 s57, 2
	s_cbranch_scc1 .Lav0_ldd
	s_add_u32 s1, s51, 2
	s_lshl_b32 s31, s1, 9
	s_mul_i32 s15, s1, s44
	s_add_u32 s15, s15, s13
	s_cmp_eq_u32 s1, 16
	s_cselect_b32 s1, s14, s15
	s_lshl_b32 s15, s1, 9
	s_add_u32 s22, s4, 0x1404c000
	s_addc_u32 s23, s5, 0
	s_add_u32 s22, s22, s15
	s_addc_u32 s23, s23, 0
	global_load_dword v40, v226, s[22:23]
	global_load_dword v41, v226, s[22:23] offset:256
	s_add_u32 s24, s4, 0x1508c000
	s_addc_u32 s25, s5, 0
	s_add_u32 s24, s24, s15
	s_addc_u32 s25, s25, 0
	global_load_dword v118, v226, s[24:25]
	global_load_dword v119, v226, s[24:25] offset:256
	v_add_u32_e32 v229, s31, v228
	ds_read_b32 v230, v229
	ds_read_b32 v231, v229 offset:256
	s_cmp_le_u32 s57, 3
	s_cbranch_scc1 .Lav0_ldd
	s_add_u32 s1, s51, 3
	s_lshl_b32 s31, s1, 9
	s_mul_i32 s15, s1, s44
	s_add_u32 s15, s15, s13
	s_cmp_eq_u32 s1, 16
	s_cselect_b32 s1, s14, s15
	s_lshl_b32 s15, s1, 9
	s_add_u32 s22, s4, 0x1404c000
	s_addc_u32 s23, s5, 0
	s_add_u32 s22, s22, s15
	s_addc_u32 s23, s23, 0
	global_load_dword v42, v226, s[22:23]
	global_load_dword v43, v226, s[22:23] offset:256
	s_add_u32 s24, s4, 0x1508c000
	s_addc_u32 s25, s5, 0
	s_add_u32 s24, s24, s15
	s_addc_u32 s25, s25, 0
	global_load_dword v120, v226, s[24:25]
	global_load_dword v121, v226, s[24:25] offset:256
	v_add_u32_e32 v229, s31, v228
	ds_read_b32 v252, v229
	ds_read_b32 v253, v229 offset:256

; __device__ __forceinline__ void ph_peer_apply(const Params& P, int layer, float* xlat, float* xctx_in, float* xctx_out, int nrows, bool write_next, char* smem, float* xlat_out = nullptr) {
;     ...
;     const float* xs1 = (row < NL ? xlat + (size_t)row * D : xctx_in + (size_t)(row - NL) * D) + lb * 32;
;     float* xo = (row < NL ? (xlat_out ? xlat_out : xlat) + (size_t)row * D : xctx_out + (size_t)(row - NL) * D) + lb * 32;
;     const float* gt = mod_ptr(P, layer, row, 5) + lb * 32;
.Lav0_lnl:
	s_add_u32 s1, s51, s63
	s_mul_i32 s15, s1, s44
	s_add_u32 s15, s15, s13
	s_cmp_eq_u32 s1, 16
	s_cselect_b32 s45, s14, s15
	s_cmp_eq_u32 s63, 1
	s_cbranch_scc1 .Lav0_cp1
	s_cmp_eq_u32 s63, 2
	s_cbranch_scc1 .Lav0_cp2
	s_cmp_eq_u32 s63, 3
	s_cbranch_scc1 .Lav0_cp3
	s_branch .Lav0_cpd

; __device__ __forceinline__ void ph_peer_apply(const Params& P, int layer, float* xlat, float* xctx_in, float* xctx_out, int nrows, bool write_next, char* smem, float* xlat_out = nullptr) {
;     ...
;   for (int row = blockIdx.x * (NTHR / 64) + wave; row < nrows; row += gridDim.x * (NTHR / 64)) {
;     float xv[32];
; #pragma unroll
;     for (int j8 = 0; j8 < 4; ++j8) {
;       const h16x8 t = *(const h16x8*)(xq + (size_t)row * D + lb * 32 + j8 * 8);
; #pragma unroll
;       for (int j = 0; j < 8; ++j) xv[j8 * 8 + j] = lact ? (float)t[j] : 0.f;
;     }
;     const int id0 = seli[(size_t)row * NSEL + lane], id1 = seli[(size_t)row * NSEL + 64 + lane];
;     const float g0 = selg[(size_t)row * NSEL + lane], g1 = selg[(size_t)row * NSEL + 64 + lane];
;     float a0 = 0.f, a1 = 0.f;
;     P6Blk bufA[PB_G], bufB[PB_G];
.Lau1_ntl:
	s_add_u32 s50, s50, 1
	s_add_u32 s1, s1, s44
	s_cmp_lt_u32 s1, 0x8000
	s_cbranch_scc1 .Lau1_ntl
	s_lshl_b32 s14, s44, 4
	s_add_u32 s14, s14, s13
	s_mov_b32 s58, 0
	s_mov_b32 s59, 0
	s_mov_b32 s62, 0
	s_mov_b32 s48, 0
	s_mov_b32 s49, 0
	s_mov_b32 s45, s13
	s_lshl_b32 s15, s45, 12
	s_lshr_b32 s31, s45, 20
	s_add_u32 s20, s4, 0xbe4c000
	s_addc_u32 s21, s5, 0
	s_add_u32 s20, s20, s15
	s_addc_u32 s21, s21, s31
	s_lshl_b32 s15, s45, 9
	s_add_u32 s22, s4, 0x1404c000
	s_addc_u32 s23, s5, 0
	s_add_u32 s22, s22, s15
	s_addc_u32 s23, s23, 0
	global_load_dwordx4 v[230:233], v224, s[20:21]
	global_load_dwordx4 v[234:237], v224, s[20:21] offset:16
	global_load_dwordx4 v[238:241], v224, s[20:21] offset:32
	global_load_dwordx4 v[242:245], v224, s[20:21] offset:48
	global_load_dword v36, v226, s[22:23]
	global_load_dword v37, v226, s[22:23] offset:256
	s_waitcnt vmcnt(0)
	v_cvt_f32_f16_e32 v4, v230
	v_cvt_f32_f16_sdwa v5, v230 dst_sel:DWORD dst_unused:UNUSED_PAD src0_sel:WORD_1
	v_cvt_f32_f16_e32 v6, v231
	v_cvt_f32_f16_sdwa v7, v231 dst_sel:DWORD dst_unused:UNUSED_PAD src0_sel:WORD_1
	v_cvt_f32_f16_e32 v8, v232
	v_cvt_f32_f16_sdwa v9, v232 dst_sel:DWORD dst_unused:UNUSED_PAD src0_sel:WORD_1
	v_cvt_f32_f16_e32 v10, v233
	v_cvt_f32_f16_sdwa v11, v233 dst_sel:DWORD dst_unused:UNUSED_PAD src0_sel:WORD_1
	v_cvt_f32_f16_e32 v12, v234
	v_cvt_f32_f16_sdwa v13, v234 dst_sel:DWORD dst_unused:UNUSED_PAD src0_sel:WORD_1
	v_cvt_f32_f16_e32 v14, v235
	v_cvt_f32_f16_sdwa v15, v235 dst_sel:DWORD dst_unused:UNUSED_PAD src0_sel:WORD_1
	v_cvt_f32_f16_e32 v16, v236
	v_cvt_f32_f16_sdwa v17, v236 dst_sel:DWORD dst_unused:UNUSED_PAD src0_sel:WORD_1
	v_cvt_f32_f16_e32 v18, v237
	v_cvt_f32_f16_sdwa v19, v237 dst_sel:DWORD dst_unused:UNUSED_PAD src0_sel:WORD_1
	v_cvt_f32_f16_e32 v20, v238
	v_cvt_f32_f16_sdwa v21, v238 dst_sel:DWORD dst_unused:UNUSED_PAD src0_sel:WORD_1
	v_cvt_f32_f16_e32 v22, v239
	v_cvt_f32_f16_sdwa v23, v239 dst_sel:DWORD dst_unused:UNUSED_PAD src0_sel:WORD_1
	v_cvt_f32_f16_e32 v24, v240
	v_cvt_f32_f16_sdwa v25, v240 dst_sel:DWORD dst_unused:UNUSED_PAD src0_sel:WORD_1
	v_cvt_f32_f16_e32 v26, v241
	v_cvt_f32_f16_sdwa v27, v241 dst_sel:DWORD dst_unused:UNUSED_PAD src0_sel:WORD_1
	v_cvt_f32_f16_e32 v28, v242
	v_cvt_f32_f16_sdwa v29, v242 dst_sel:DWORD dst_unused:UNUSED_PAD src0_sel:WORD_1
	v_cvt_f32_f16_e32 v30, v243
	v_cvt_f32_f16_sdwa v31, v243 dst_sel:DWORD dst_unused:UNUSED_PAD src0_sel:WORD_1
	v_cvt_f32_f16_e32 v32, v244
	v_cvt_f32_f16_sdwa v33, v244 dst_sel:DWORD dst_unused:UNUSED_PAD src0_sel:WORD_1
	v_cvt_f32_f16_e32 v34, v245
	v_cvt_f32_f16_sdwa v35, v245 dst_sel:DWORD dst_unused:UNUSED_PAD src0_sel:WORD_1
	v_lshrrev_b32_e32 v249, 11, v36
	v_lshrrev_b32_e32 v250, 11, v37
	v_cmp_eq_u32_e64 s[52:53], s58, v249
	v_cmp_eq_u32_e64 s[54:55], s58, v250
	v_mul_u32_u24_e32 v44, 0x640, v36
	s_mov_b32 s61, 0
	s_lshl_b32 s63, s59, 9
	s_mul_i32 s1, s12, 0x2800
	s_add_u32 s63, s63, s1
	v_add_u32_e32 v46, s63, v226
	s_bcnt1_i32_b64 s1, s[52:53]
	s_bcnt1_i32_b64 s15, s[54:55]
	s_add_u32 s1, s1, s15
	s_sub_u32 s57, 8, s1
	s_cselect_b32 s57, 0, s57
	s_add_u32 s1, s59, 1
	s_cmp_lt_u32 s1, s50
	s_cbranch_scc1 .Lau1_pfki
	s_mov_b32 s1, 0
	s_cmp_lt_u32 s58, 7
	s_cbranch_scc0 .Lau1_pfdi

; #define PB_FENCE asm volatile("" ::: "memory")
; __device__ __forceinline__ void ph_peer_apply(const Params& P, int layer, float* xlat, float* xctx_in, float* xctx_out, int nrows, bool write_next, char* smem, float* xlat_out = nullptr) {
;     ...
;     PB_LOAD(bufA, tv, 0);
;     for (int gq = 0; gq < NG; gq += 2) {
;       PB_LOAD(bufB, tv, gq + 1); PB_FENCE;
.Lav1_ntl:
	s_add_u32 s62, s62, 1
	s_add_u32 s1, s1, s44
	s_cmp_lt_u32 s1, 0x8000
	s_cbranch_scc1 .Lav1_ntl
	s_lshl_b32 s14, s44, 4
	s_add_u32 s14, s14, s13
	s_mov_b32 s51, 0
